# v57 + retention staging loads in scalar-base plus 32-bit lane-offset form (uniform address math on the SALU, one lane offset per step)
# baseline (speedup 1.0000x reference)
.Lra_noq:
	ds_write_b128 v249, v[184:187] offset:34816
	ds_write_b128 v249, v[188:191] offset:43008
	ds_write_b128 v249, v[180:183] offset:51200
	ds_write_b128 v249, v[176:179] offset:59392
	s_and_b64 vcc, exec, s[54:55]
	s_cselect_b64 s[14:15], s[40:41], s[30:31]
	s_lshl_b32 s28, s18, 7
	s_ashr_i32 s34, s28, 31
	s_add_u32 s18, s14, s28
	s_addc_u32 s19, s15, s34
	s_lshl_b64 s[14:15], s[18:19], 11
	s_add_u32 s14, s38, s14
	s_addc_u32 s15, s39, s15
	s_lshl_b64 s[18:19], s[18:19], 11
	s_add_u32 s18, s36, s18
	s_addc_u32 s19, s37, s19
	s_and_b64 s[96:97], s[44:45], exec
	s_mov_b32 s32, 0xffff0000
	s_cselect_b32 s32, 0x10000, s32
	v_sub_u32_e32 v2, 0x7f, v202
	v_lshlrev_b32_e32 v3, 1, v203
	v_cndmask_b32_e64 v2, v2, v202, s[44:45]
	v_lshl_or_b32 v2, v2, 11, v3
	v_add_u32_e32 v3, s32, v2
	v_add_u32_e32 v4, s32, v3
	v_add_u32_e32 v5, s32, v4
	s_and_b64 vcc, exec, s[16:17]
	s_cbranch_vccnz .Lra_l1
	global_load_dwordx4 v[156:159], v2, s[14:15] offset:256
.Lra_l1:
	global_load_dwordx4 v[184:187], v2, s[18:19] offset:256
	s_cbranch_vccnz .Lra_l2
	global_load_dwordx4 v[152:155], v3, s[14:15] offset:256
.Lra_l2:
	global_load_dwordx4 v[188:191], v3, s[18:19] offset:256
	s_cbranch_vccnz .Lra_l3
	global_load_dwordx4 v[148:151], v4, s[14:15] offset:256
.Lra_l3:
	global_load_dwordx4 v[180:183], v4, s[18:19] offset:256
	s_cbranch_vccnz .Lra_l4
	global_load_dwordx4 v[144:147], v5, s[14:15] offset:256
.Lra_l4:
	global_load_dwordx4 v[176:179], v5, s[18:19] offset:256
	s_and_b64 vcc, exec, s[54:55]
	s_cbranch_vccz .LBB0_898
	s_waitcnt lgkmcnt(0)
	v_mad_u64_u32 v[2:3], s[14:15], v197, s68, v[192:193]

.LBB0_931:
	s_cmp_lg_u32 s49, 17
	s_cselect_b64 s[56:57], -1, 0
	s_sub_i32 s33, 16, s49
	s_cmp_eq_u32 s49, 17
	s_cbranch_scc1 .LBB0_941
	s_add_i32 s82, s49, -1
	s_and_b64 s[96:97], s[44:45], exec
	s_cselect_b32 s82, s82, s33
	s_mov_b32 s32, 0xffff0000
	s_cselect_b32 s32, 0x10000, s32
	s_lshl_b32 s82, s82, 7
	s_add_u32 s82, s40, s82
	s_addc_u32 s83, s41, 0
	s_and_b64 s[96:97], s[14:15], exec
	s_cselect_b32 s82, s52, s82
	s_cselect_b32 s83, s53, s83
	s_lshl_b64 s[82:83], s[82:83], 11
	s_add_u32 s96, s38, s82
	s_addc_u32 s97, s39, s83
	s_add_u32 s82, s36, s82
	s_addc_u32 s83, s37, s83
	v_sub_u32_e32 v2, 0x7f, v202
	v_lshlrev_b32_e32 v3, 1, v203
	v_cndmask_b32_e64 v2, v2, v202, s[44:45]
	v_lshl_or_b32 v2, v2, 11, v3
	v_add_u32_e32 v3, s32, v2
	v_add_u32_e32 v4, s32, v3
	v_add_u32_e32 v5, s32, v4
	s_and_b64 vcc, exec, s[14:15]
	s_cbranch_vccnz .Lrc_l1
	global_load_dwordx4 v[156:159], v2, s[96:97]
.Lrc_l1:
	global_load_dwordx4 v[184:187], v2, s[82:83]
	s_cbranch_vccnz .Lrc_l2
	global_load_dwordx4 v[152:155], v3, s[96:97]
.Lrc_l2:
	global_load_dwordx4 v[188:191], v3, s[82:83]
	s_cbranch_vccnz .Lrc_l3
	global_load_dwordx4 v[148:151], v4, s[96:97]
.Lrc_l3:
	global_load_dwordx4 v[180:183], v4, s[82:83]
	s_cbranch_vccnz .Lrc_l4
	global_load_dwordx4 v[144:147], v5, s[96:97]
.Lrc_l4:
	global_load_dwordx4 v[176:179], v5, s[82:83]

.Lre_m2:
	s_or_b64 exec, exec, s[16:17]
	v_cvt_pk_bf16_f32 v8, v112, v113
	v_cvt_pk_bf16_f32 v9, v114, v115
	ds_write_b64 v3, v[8:9]
	v_cvt_pk_bf16_f32 v12, v116, v117
	v_cvt_pk_bf16_f32 v13, v118, v119
	ds_write_b64 v3, v[12:13] offset:16
	v_cvt_pk_bf16_f32 v8, v120, v121
	v_cvt_pk_bf16_f32 v9, v122, v123
	ds_write_b64 v3, v[8:9] offset:32
	v_cvt_pk_bf16_f32 v12, v124, v125
	v_cvt_pk_bf16_f32 v13, v126, v127
	ds_write_b64 v3, v[12:13] offset:48
	s_and_b64 vcc, exec, s[56:57]
	s_waitcnt lgkmcnt(0)
	s_barrier
	s_cbranch_vccz .LBB0_974
	s_add_i32 s82, s49, -1
	s_and_b64 s[96:97], s[44:45], exec
	s_cselect_b32 s82, s82, s33
	s_mov_b32 s32, 0xfffe0000
	s_cselect_b32 s32, 0x20000, s32
	s_lshl_b32 s82, s82, 19
	s_add_u32 s82, s42, s82
	s_addc_u32 s83, s43, 0
	v_sub_u32_e32 v2, 0x7f, v202
	v_lshlrev_b32_e32 v3, 1, v203
	v_cndmask_b32_e64 v2, v2, v202, s[44:45]
	v_lshl_or_b32 v2, v2, 12, v3
	v_add_u32_e32 v3, s32, v2
	v_add_u32_e32 v4, s32, v3
	v_add_u32_e32 v5, s32, v4
	global_load_dwordx4 v[160:163], v2, s[82:83]
	global_load_dwordx4 v[164:167], v3, s[82:83]
	global_load_dwordx4 v[168:171], v4, s[82:83]
	global_load_dwordx4 v[172:175], v5, s[82:83]
.LBB0_974:
	s_and_b64 vcc, exec, s[46:47]
	s_cbranch_vccz .Lret_nopf
	s_add_u32 s16, s40, s28
	s_addc_u32 s17, s41, s34
	s_lshl_b64 s[16:17], s[16:17], 12
	s_or_b32 s16, s16, s80
	s_add_u32 s16, s26, s16
	s_addc_u32 s17, s27, s17
	v_sub_u32_e32 v2, 0x7f, v197
	v_lshlrev_b32_e32 v3, 1, v203
	v_lshl_or_b32 v2, v2, 12, v3
	global_load_dwordx4 v[124:127], v2, s[16:17]
	v_add_u32_e32 v3, 0xfffe0000, v2
	global_load_dwordx4 v[128:131], v3, s[16:17]
	v_add_u32_e32 v4, 0xfffe0000, v3
	global_load_dwordx4 v[132:135], v4, s[16:17]
	v_add_u32_e32 v5, 0xfffe0000, v4
	global_load_dwordx4 v[136:139], v5, s[16:17]
